# GEMM K-loop heads pinned to the baseline build's 64-byte phases; attention loops at 48/16
# speedup vs baseline: 1.0065x; 1.0065x over previous
.LBB0_154:
	s_ashr_i32 s25, s24, 31
	s_lshl_b64 s[26:27], s[24:25], 19
	s_add_u32 s26, s34, s26
	s_addc_u32 s27, s35, s27
	s_and_b64 s[28:29], s[4:5], exec
	s_cselect_b32 s25, s27, s3
	s_cselect_b32 s48, s26, s2
	s_ashr_i32 s23, s22, 31
	s_lshl_b64 s[28:29], s[22:23], 19
	s_add_u32 s28, s33, s28
	s_addc_u32 s29, s36, s29
	s_and_b64 s[30:31], s[4:5], exec
	s_cselect_b32 s23, s29, s7
	s_cselect_b32 s49, s28, s6
	s_add_u32 s2, s2, 0x40080
	s_addc_u32 s3, s3, 0
	s_add_u32 s50, s6, 0x100
	v_mov_b32_e32 v0, 0
	s_addc_u32 s51, s7, 0
	s_mov_b32 s52, -2
	v_mov_b32_e32 v1, v0
	v_mov_b32_e32 v2, v0
	v_mov_b32_e32 v3, v0
	v_mov_b32_e32 v4, v0
	v_mov_b32_e32 v5, v0
	v_mov_b32_e32 v6, v0
	v_mov_b32_e32 v7, v0
	v_mov_b32_e32 v16, v0
	v_mov_b32_e32 v17, v0
	v_mov_b32_e32 v18, v0
	v_mov_b32_e32 v19, v0
	v_mov_b32_e32 v20, v0
	v_mov_b32_e32 v21, v0
	v_mov_b32_e32 v22, v0
	v_mov_b32_e32 v23, v0
	v_mov_b32_e32 v32, v0
	v_mov_b32_e32 v33, v0
	v_mov_b32_e32 v34, v0
	v_mov_b32_e32 v35, v0
	v_mov_b32_e32 v36, v0
	v_mov_b32_e32 v37, v0
	v_mov_b32_e32 v38, v0
	v_mov_b32_e32 v39, v0
	v_mov_b32_e32 v48, v0
	v_mov_b32_e32 v49, v0
	v_mov_b32_e32 v50, v0
	v_mov_b32_e32 v51, v0
	v_mov_b32_e32 v52, v0
	v_mov_b32_e32 v53, v0
	v_mov_b32_e32 v54, v0
	v_mov_b32_e32 v55, v0
	v_mov_b32_e32 v8, v0
	v_mov_b32_e32 v9, v0
	v_mov_b32_e32 v10, v0
	v_mov_b32_e32 v11, v0
	v_mov_b32_e32 v12, v0
	v_mov_b32_e32 v13, v0
	v_mov_b32_e32 v14, v0
	v_mov_b32_e32 v15, v0
	v_mov_b32_e32 v24, v0
	v_mov_b32_e32 v25, v0
	v_mov_b32_e32 v26, v0
	v_mov_b32_e32 v27, v0
	v_mov_b32_e32 v28, v0
	v_mov_b32_e32 v29, v0
	v_mov_b32_e32 v30, v0
	v_mov_b32_e32 v31, v0
	v_mov_b32_e32 v40, v0
	v_mov_b32_e32 v41, v0
	v_mov_b32_e32 v42, v0
	v_mov_b32_e32 v43, v0
	v_mov_b32_e32 v44, v0
	v_mov_b32_e32 v45, v0
	v_mov_b32_e32 v46, v0
	v_mov_b32_e32 v47, v0
	v_mov_b32_e32 v56, v0
	v_mov_b32_e32 v57, v0
	v_mov_b32_e32 v58, v0
	v_mov_b32_e32 v59, v0
	v_mov_b32_e32 v60, v0
	v_mov_b32_e32 v61, v0
	v_mov_b32_e32 v62, v0
	v_mov_b32_e32 v63, v0
	v_mov_b32_e32 v64, v0
	v_mov_b32_e32 v65, v0
	v_mov_b32_e32 v66, v0
	v_mov_b32_e32 v67, v0
	v_mov_b32_e32 v68, v0
	v_mov_b32_e32 v69, v0
	v_mov_b32_e32 v70, v0
	v_mov_b32_e32 v71, v0
	v_mov_b32_e32 v80, v0
	v_mov_b32_e32 v81, v0
	v_mov_b32_e32 v82, v0
	v_mov_b32_e32 v83, v0
	v_mov_b32_e32 v84, v0
	v_mov_b32_e32 v85, v0
	v_mov_b32_e32 v86, v0
	v_mov_b32_e32 v87, v0
	v_mov_b32_e32 v96, v0
	v_mov_b32_e32 v97, v0
	v_mov_b32_e32 v98, v0
	v_mov_b32_e32 v99, v0
	v_mov_b32_e32 v100, v0
	v_mov_b32_e32 v101, v0
	v_mov_b32_e32 v102, v0
	v_mov_b32_e32 v103, v0
	v_mov_b32_e32 v112, v0
	v_mov_b32_e32 v113, v0
	v_mov_b32_e32 v114, v0
	v_mov_b32_e32 v115, v0
	v_mov_b32_e32 v116, v0
	v_mov_b32_e32 v117, v0
	v_mov_b32_e32 v118, v0
	v_mov_b32_e32 v119, v0
	v_mov_b32_e32 v72, v0
	v_mov_b32_e32 v73, v0
	v_mov_b32_e32 v74, v0
	v_mov_b32_e32 v75, v0
	v_mov_b32_e32 v76, v0
	v_mov_b32_e32 v77, v0
	v_mov_b32_e32 v78, v0
	v_mov_b32_e32 v79, v0
	v_mov_b32_e32 v88, v0
	v_mov_b32_e32 v89, v0
	v_mov_b32_e32 v90, v0
	v_mov_b32_e32 v91, v0
	v_mov_b32_e32 v92, v0
	v_mov_b32_e32 v93, v0
	v_mov_b32_e32 v94, v0
	v_mov_b32_e32 v95, v0
	v_mov_b32_e32 v104, v0
	v_mov_b32_e32 v105, v0
	v_mov_b32_e32 v106, v0
	v_mov_b32_e32 v107, v0
	v_mov_b32_e32 v108, v0
	v_mov_b32_e32 v109, v0
	v_mov_b32_e32 v110, v0
	v_mov_b32_e32 v111, v0
	v_mov_b32_e32 v120, v0
	v_mov_b32_e32 v121, v0
	v_mov_b32_e32 v122, v0
	v_mov_b32_e32 v123, v0
	v_mov_b32_e32 v124, v0
	v_mov_b32_e32 v125, v0
	v_mov_b32_e32 v126, v0
	v_mov_b32_e32 v127, v0
	.p2align 6
	s_nop 0
	s_nop 0
	s_nop 0
	s_nop 0
	s_nop 0
	s_nop 0
	s_nop 0
	s_nop 0
	s_nop 0
	s_nop 0
	s_nop 0
	s_nop 0

.LBB0_224:
	s_ashr_i32 s11, s10, 31
	s_lshl_b64 s[12:13], s[10:11], 19
	s_add_u32 s12, s22, s12
	s_addc_u32 s13, s23, s13
	s_and_b64 s[14:15], s[4:5], exec
	s_cselect_b32 s11, s13, s17
	s_cselect_b32 s37, s12, s16
	s_ashr_i32 s9, s8, 31
	s_lshl_b64 s[14:15], s[8:9], 19
	s_add_u32 s14, s34, s14
	s_addc_u32 s15, s35, s15
	s_and_b64 s[20:21], s[4:5], exec
	s_cselect_b32 s9, s15, s19
	s_cselect_b32 s38, s14, s18
	s_add_u32 s16, s16, 0x40080
	s_addc_u32 s17, s17, 0
	s_add_u32 s39, s18, 0x100
	v_mov_b32_e32 v0, 0
	s_addc_u32 s40, s19, 0
	s_mov_b32 s41, -2
	v_mov_b32_e32 v1, v0
	v_mov_b32_e32 v2, v0
	v_mov_b32_e32 v3, v0
	v_mov_b32_e32 v4, v0
	v_mov_b32_e32 v5, v0
	v_mov_b32_e32 v6, v0
	v_mov_b32_e32 v7, v0
	v_mov_b32_e32 v8, v0
	v_mov_b32_e32 v9, v0
	v_mov_b32_e32 v10, v0
	v_mov_b32_e32 v11, v0
	v_mov_b32_e32 v12, v0
	v_mov_b32_e32 v13, v0
	v_mov_b32_e32 v14, v0
	v_mov_b32_e32 v15, v0
	v_mov_b32_e32 v24, v0
	v_mov_b32_e32 v25, v0
	v_mov_b32_e32 v26, v0
	v_mov_b32_e32 v27, v0
	v_mov_b32_e32 v28, v0
	v_mov_b32_e32 v29, v0
	v_mov_b32_e32 v30, v0
	v_mov_b32_e32 v31, v0
	v_mov_b32_e32 v40, v0
	v_mov_b32_e32 v41, v0
	v_mov_b32_e32 v42, v0
	v_mov_b32_e32 v43, v0
	v_mov_b32_e32 v44, v0
	v_mov_b32_e32 v45, v0
	v_mov_b32_e32 v46, v0
	v_mov_b32_e32 v47, v0
	v_mov_b32_e32 v16, v0
	v_mov_b32_e32 v17, v0
	v_mov_b32_e32 v18, v0
	v_mov_b32_e32 v19, v0
	v_mov_b32_e32 v20, v0
	v_mov_b32_e32 v21, v0
	v_mov_b32_e32 v22, v0
	v_mov_b32_e32 v23, v0
	v_mov_b32_e32 v32, v0
	v_mov_b32_e32 v33, v0
	v_mov_b32_e32 v34, v0
	v_mov_b32_e32 v35, v0
	v_mov_b32_e32 v36, v0
	v_mov_b32_e32 v37, v0
	v_mov_b32_e32 v38, v0
	v_mov_b32_e32 v39, v0
	v_mov_b32_e32 v48, v0
	v_mov_b32_e32 v49, v0
	v_mov_b32_e32 v50, v0
	v_mov_b32_e32 v51, v0
	v_mov_b32_e32 v52, v0
	v_mov_b32_e32 v53, v0
	v_mov_b32_e32 v54, v0
	v_mov_b32_e32 v55, v0
	v_mov_b32_e32 v56, v0
	v_mov_b32_e32 v57, v0
	v_mov_b32_e32 v58, v0
	v_mov_b32_e32 v59, v0
	v_mov_b32_e32 v60, v0
	v_mov_b32_e32 v61, v0
	v_mov_b32_e32 v62, v0
	v_mov_b32_e32 v63, v0
	v_mov_b32_e32 v64, v0
	v_mov_b32_e32 v65, v0
	v_mov_b32_e32 v66, v0
	v_mov_b32_e32 v67, v0
	v_mov_b32_e32 v68, v0
	v_mov_b32_e32 v69, v0
	v_mov_b32_e32 v70, v0
	v_mov_b32_e32 v71, v0
	v_mov_b32_e32 v72, v0
	v_mov_b32_e32 v73, v0
	v_mov_b32_e32 v74, v0
	v_mov_b32_e32 v75, v0
	v_mov_b32_e32 v76, v0
	v_mov_b32_e32 v77, v0
	v_mov_b32_e32 v78, v0
	v_mov_b32_e32 v79, v0
	v_mov_b32_e32 v88, v0
	v_mov_b32_e32 v89, v0
	v_mov_b32_e32 v90, v0
	v_mov_b32_e32 v91, v0
	v_mov_b32_e32 v92, v0
	v_mov_b32_e32 v93, v0
	v_mov_b32_e32 v94, v0
	v_mov_b32_e32 v95, v0
	v_mov_b32_e32 v104, v0
	v_mov_b32_e32 v105, v0
	v_mov_b32_e32 v106, v0
	v_mov_b32_e32 v107, v0
	v_mov_b32_e32 v108, v0
	v_mov_b32_e32 v109, v0
	v_mov_b32_e32 v110, v0
	v_mov_b32_e32 v111, v0
	v_mov_b32_e32 v80, v0
	v_mov_b32_e32 v81, v0
	v_mov_b32_e32 v82, v0
	v_mov_b32_e32 v83, v0
	v_mov_b32_e32 v84, v0
	v_mov_b32_e32 v85, v0
	v_mov_b32_e32 v86, v0
	v_mov_b32_e32 v87, v0
	v_mov_b32_e32 v96, v0
	v_mov_b32_e32 v97, v0
	v_mov_b32_e32 v98, v0
	v_mov_b32_e32 v99, v0
	v_mov_b32_e32 v100, v0
	v_mov_b32_e32 v101, v0
	v_mov_b32_e32 v102, v0
	v_mov_b32_e32 v103, v0
	v_mov_b32_e32 v112, v0
	v_mov_b32_e32 v113, v0
	v_mov_b32_e32 v114, v0
	v_mov_b32_e32 v115, v0
	v_mov_b32_e32 v116, v0
	v_mov_b32_e32 v117, v0
	v_mov_b32_e32 v118, v0
	v_mov_b32_e32 v119, v0
	v_mov_b32_e32 v120, v0
	v_mov_b32_e32 v121, v0
	v_mov_b32_e32 v122, v0
	v_mov_b32_e32 v123, v0
	v_mov_b32_e32 v124, v0
	v_mov_b32_e32 v125, v0
	v_mov_b32_e32 v126, v0
	v_mov_b32_e32 v127, v0
	.p2align 6
	s_nop 0

.LBB0_630:
	s_ashr_i32 s17, s16, 31
	s_lshl_b64 s[18:19], s[16:17], 19
	s_add_u32 s18, s28, s18
	s_addc_u32 s19, s29, s19
	s_and_b64 s[20:21], s[4:5], exec
	s_cselect_b32 s17, s19, s23
	s_cselect_b32 s43, s18, s22
	s_ashr_i32 s15, s14, 31
	s_lshl_b64 s[20:21], s[14:15], 19
	s_add_u32 s20, s30, s20
	s_addc_u32 s21, s31, s21
	s_and_b64 s[26:27], s[4:5], exec
	s_cselect_b32 s15, s21, s25
	s_cselect_b32 s44, s20, s24
	s_add_u32 s22, s22, 0x40080
	s_addc_u32 s23, s23, 0
	s_add_u32 s45, s24, 0x100
	v_mov_b32_e32 v0, 0
	s_addc_u32 s46, s25, 0
	s_mov_b32 s47, -2
	v_mov_b32_e32 v1, v0
	v_mov_b32_e32 v2, v0
	v_mov_b32_e32 v3, v0
	v_mov_b32_e32 v4, v0
	v_mov_b32_e32 v5, v0
	v_mov_b32_e32 v6, v0
	v_mov_b32_e32 v7, v0
	v_mov_b32_e32 v16, v0
	v_mov_b32_e32 v17, v0
	v_mov_b32_e32 v18, v0
	v_mov_b32_e32 v19, v0
	v_mov_b32_e32 v20, v0
	v_mov_b32_e32 v21, v0
	v_mov_b32_e32 v22, v0
	v_mov_b32_e32 v23, v0
	v_mov_b32_e32 v32, v0
	v_mov_b32_e32 v33, v0
	v_mov_b32_e32 v34, v0
	v_mov_b32_e32 v35, v0
	v_mov_b32_e32 v36, v0
	v_mov_b32_e32 v37, v0
	v_mov_b32_e32 v38, v0
	v_mov_b32_e32 v39, v0
	v_mov_b32_e32 v48, v0
	v_mov_b32_e32 v49, v0
	v_mov_b32_e32 v50, v0
	v_mov_b32_e32 v51, v0
	v_mov_b32_e32 v52, v0
	v_mov_b32_e32 v53, v0
	v_mov_b32_e32 v54, v0
	v_mov_b32_e32 v55, v0
	v_mov_b32_e32 v8, v0
	v_mov_b32_e32 v9, v0
	v_mov_b32_e32 v10, v0
	v_mov_b32_e32 v11, v0
	v_mov_b32_e32 v12, v0
	v_mov_b32_e32 v13, v0
	v_mov_b32_e32 v14, v0
	v_mov_b32_e32 v15, v0
	v_mov_b32_e32 v24, v0
	v_mov_b32_e32 v25, v0
	v_mov_b32_e32 v26, v0
	v_mov_b32_e32 v27, v0
	v_mov_b32_e32 v28, v0
	v_mov_b32_e32 v29, v0
	v_mov_b32_e32 v30, v0
	v_mov_b32_e32 v31, v0
	v_mov_b32_e32 v40, v0
	v_mov_b32_e32 v41, v0
	v_mov_b32_e32 v42, v0
	v_mov_b32_e32 v43, v0
	v_mov_b32_e32 v44, v0
	v_mov_b32_e32 v45, v0
	v_mov_b32_e32 v46, v0
	v_mov_b32_e32 v47, v0
	v_mov_b32_e32 v56, v0
	v_mov_b32_e32 v57, v0
	v_mov_b32_e32 v58, v0
	v_mov_b32_e32 v59, v0
	v_mov_b32_e32 v60, v0
	v_mov_b32_e32 v61, v0
	v_mov_b32_e32 v62, v0
	v_mov_b32_e32 v63, v0
	v_mov_b32_e32 v64, v0
	v_mov_b32_e32 v65, v0
	v_mov_b32_e32 v66, v0
	v_mov_b32_e32 v67, v0
	v_mov_b32_e32 v68, v0
	v_mov_b32_e32 v69, v0
	v_mov_b32_e32 v70, v0
	v_mov_b32_e32 v71, v0
	v_mov_b32_e32 v80, v0
	v_mov_b32_e32 v81, v0
	v_mov_b32_e32 v82, v0
	v_mov_b32_e32 v83, v0
	v_mov_b32_e32 v84, v0
	v_mov_b32_e32 v85, v0
	v_mov_b32_e32 v86, v0
	v_mov_b32_e32 v87, v0
	v_mov_b32_e32 v96, v0
	v_mov_b32_e32 v97, v0
	v_mov_b32_e32 v98, v0
	v_mov_b32_e32 v99, v0
	v_mov_b32_e32 v100, v0
	v_mov_b32_e32 v101, v0
	v_mov_b32_e32 v102, v0
	v_mov_b32_e32 v103, v0
	v_mov_b32_e32 v112, v0
	v_mov_b32_e32 v113, v0
	v_mov_b32_e32 v114, v0
	v_mov_b32_e32 v115, v0
	v_mov_b32_e32 v116, v0
	v_mov_b32_e32 v117, v0
	v_mov_b32_e32 v118, v0
	v_mov_b32_e32 v119, v0
	v_mov_b32_e32 v72, v0
	v_mov_b32_e32 v73, v0
	v_mov_b32_e32 v74, v0
	v_mov_b32_e32 v75, v0
	v_mov_b32_e32 v76, v0
	v_mov_b32_e32 v77, v0
	v_mov_b32_e32 v78, v0
	v_mov_b32_e32 v79, v0
	v_mov_b32_e32 v88, v0
	v_mov_b32_e32 v89, v0
	v_mov_b32_e32 v90, v0
	v_mov_b32_e32 v91, v0
	v_mov_b32_e32 v92, v0
	v_mov_b32_e32 v93, v0
	v_mov_b32_e32 v94, v0
	v_mov_b32_e32 v95, v0
	v_mov_b32_e32 v104, v0
	v_mov_b32_e32 v105, v0
	v_mov_b32_e32 v106, v0
	v_mov_b32_e32 v107, v0
	v_mov_b32_e32 v108, v0
	v_mov_b32_e32 v109, v0
	v_mov_b32_e32 v110, v0
	v_mov_b32_e32 v111, v0
	v_mov_b32_e32 v120, v0
	v_mov_b32_e32 v121, v0
	v_mov_b32_e32 v122, v0
	v_mov_b32_e32 v123, v0
	v_mov_b32_e32 v124, v0
	v_mov_b32_e32 v125, v0
	v_mov_b32_e32 v126, v0
	v_mov_b32_e32 v127, v0
	.p2align 6
	s_nop 0
	s_nop 0
	s_nop 0
	s_nop 0
	s_nop 0
	s_nop 0
	s_nop 0
	s_nop 0
	s_nop 0
	s_nop 0
	s_nop 0

.LBB0_650:
	s_ashr_i32 s17, s16, 31
	s_lshl_b64 s[18:19], s[16:17], 19
	s_add_u32 s18, s26, s18
	s_addc_u32 s19, s27, s19
	s_and_b64 s[20:21], s[6:7], exec
	s_cselect_b32 s17, s19, s3
	s_cselect_b32 s41, s18, s2
	s_ashr_i32 s15, s14, 31
	s_lshl_b64 s[20:21], s[14:15], 19
	s_add_u32 s20, s28, s20
	s_addc_u32 s21, s29, s21
	s_and_b64 s[24:25], s[6:7], exec
	s_cselect_b32 s15, s21, s23
	s_cselect_b32 s42, s20, s22
	s_add_u32 s2, s2, 0x40080
	s_addc_u32 s3, s3, 0
	s_add_u32 s43, s22, 0x100
	v_mov_b32_e32 v0, 0
	s_addc_u32 s44, s23, 0
	s_mov_b32 s45, -2
	v_mov_b32_e32 v1, v0
	v_mov_b32_e32 v2, v0
	v_mov_b32_e32 v3, v0
	v_mov_b32_e32 v4, v0
	v_mov_b32_e32 v5, v0
	v_mov_b32_e32 v6, v0
	v_mov_b32_e32 v7, v0
	v_mov_b32_e32 v16, v0
	v_mov_b32_e32 v17, v0
	v_mov_b32_e32 v18, v0
	v_mov_b32_e32 v19, v0
	v_mov_b32_e32 v20, v0
	v_mov_b32_e32 v21, v0
	v_mov_b32_e32 v22, v0
	v_mov_b32_e32 v23, v0
	v_mov_b32_e32 v32, v0
	v_mov_b32_e32 v33, v0
	v_mov_b32_e32 v34, v0
	v_mov_b32_e32 v35, v0
	v_mov_b32_e32 v36, v0
	v_mov_b32_e32 v37, v0
	v_mov_b32_e32 v38, v0
	v_mov_b32_e32 v39, v0
	v_mov_b32_e32 v48, v0
	v_mov_b32_e32 v49, v0
	v_mov_b32_e32 v50, v0
	v_mov_b32_e32 v51, v0
	v_mov_b32_e32 v52, v0
	v_mov_b32_e32 v53, v0
	v_mov_b32_e32 v54, v0
	v_mov_b32_e32 v55, v0
	v_mov_b32_e32 v8, v0
	v_mov_b32_e32 v9, v0
	v_mov_b32_e32 v10, v0
	v_mov_b32_e32 v11, v0
	v_mov_b32_e32 v12, v0
	v_mov_b32_e32 v13, v0
	v_mov_b32_e32 v14, v0
	v_mov_b32_e32 v15, v0
	v_mov_b32_e32 v24, v0
	v_mov_b32_e32 v25, v0
	v_mov_b32_e32 v26, v0
	v_mov_b32_e32 v27, v0
	v_mov_b32_e32 v28, v0
	v_mov_b32_e32 v29, v0
	v_mov_b32_e32 v30, v0
	v_mov_b32_e32 v31, v0
	v_mov_b32_e32 v40, v0
	v_mov_b32_e32 v41, v0
	v_mov_b32_e32 v42, v0
	v_mov_b32_e32 v43, v0
	v_mov_b32_e32 v44, v0
	v_mov_b32_e32 v45, v0
	v_mov_b32_e32 v46, v0
	v_mov_b32_e32 v47, v0
	v_mov_b32_e32 v56, v0
	v_mov_b32_e32 v57, v0
	v_mov_b32_e32 v58, v0
	v_mov_b32_e32 v59, v0
	v_mov_b32_e32 v60, v0
	v_mov_b32_e32 v61, v0
	v_mov_b32_e32 v62, v0
	v_mov_b32_e32 v63, v0
	v_mov_b32_e32 v64, v0
	v_mov_b32_e32 v65, v0
	v_mov_b32_e32 v66, v0
	v_mov_b32_e32 v67, v0
	v_mov_b32_e32 v68, v0
	v_mov_b32_e32 v69, v0
	v_mov_b32_e32 v70, v0
	v_mov_b32_e32 v71, v0
	v_mov_b32_e32 v80, v0
	v_mov_b32_e32 v81, v0
	v_mov_b32_e32 v82, v0
	v_mov_b32_e32 v83, v0
	v_mov_b32_e32 v84, v0
	v_mov_b32_e32 v85, v0
	v_mov_b32_e32 v86, v0
	v_mov_b32_e32 v87, v0
	v_mov_b32_e32 v96, v0
	v_mov_b32_e32 v97, v0
	v_mov_b32_e32 v98, v0
	v_mov_b32_e32 v99, v0
	v_mov_b32_e32 v100, v0
	v_mov_b32_e32 v101, v0
	v_mov_b32_e32 v102, v0
	v_mov_b32_e32 v103, v0
	v_mov_b32_e32 v112, v0
	v_mov_b32_e32 v113, v0
	v_mov_b32_e32 v114, v0
	v_mov_b32_e32 v115, v0
	v_mov_b32_e32 v116, v0
	v_mov_b32_e32 v117, v0
	v_mov_b32_e32 v118, v0
	v_mov_b32_e32 v119, v0
	v_mov_b32_e32 v72, v0
	v_mov_b32_e32 v73, v0
	v_mov_b32_e32 v74, v0
	v_mov_b32_e32 v75, v0
	v_mov_b32_e32 v76, v0
	v_mov_b32_e32 v77, v0
	v_mov_b32_e32 v78, v0
	v_mov_b32_e32 v79, v0
	v_mov_b32_e32 v88, v0
	v_mov_b32_e32 v89, v0
	v_mov_b32_e32 v90, v0
	v_mov_b32_e32 v91, v0
	v_mov_b32_e32 v92, v0
	v_mov_b32_e32 v93, v0
	v_mov_b32_e32 v94, v0
	v_mov_b32_e32 v95, v0
	v_mov_b32_e32 v104, v0
	v_mov_b32_e32 v105, v0
	v_mov_b32_e32 v106, v0
	v_mov_b32_e32 v107, v0
	v_mov_b32_e32 v108, v0
	v_mov_b32_e32 v109, v0
	v_mov_b32_e32 v110, v0
	v_mov_b32_e32 v111, v0
	v_mov_b32_e32 v120, v0
	v_mov_b32_e32 v121, v0
	v_mov_b32_e32 v122, v0
	v_mov_b32_e32 v123, v0
	v_mov_b32_e32 v124, v0
	v_mov_b32_e32 v125, v0
	v_mov_b32_e32 v126, v0
	v_mov_b32_e32 v127, v0
	.p2align 6
	s_nop 0
	s_nop 0

.LBB0_723:
	s_ashr_i32 s13, s12, 31
	s_lshl_b64 s[14:15], s[12:13], 19
	s_add_u32 s14, s24, s14
	s_addc_u32 s15, s25, s15
	s_and_b64 s[16:17], s[4:5], exec
	s_cselect_b32 s13, s15, s19
	s_cselect_b32 s39, s14, s18
	s_ashr_i32 s11, s10, 31
	s_lshl_b64 s[16:17], s[10:11], 19
	s_add_u32 s16, s26, s16
	s_addc_u32 s17, s27, s17
	s_and_b64 s[22:23], s[4:5], exec
	s_cselect_b32 s11, s17, s21
	s_cselect_b32 s40, s16, s20
	s_add_u32 s18, s18, 0x40080
	s_addc_u32 s19, s19, 0
	s_add_u32 s41, s20, 0x100
	v_mov_b32_e32 v0, 0
	s_addc_u32 s42, s21, 0
	s_mov_b32 s43, -2
	v_mov_b32_e32 v1, v0
	v_mov_b32_e32 v2, v0
	v_mov_b32_e32 v3, v0
	v_mov_b32_e32 v4, v0
	v_mov_b32_e32 v5, v0
	v_mov_b32_e32 v6, v0
	v_mov_b32_e32 v7, v0
	v_mov_b32_e32 v16, v0
	v_mov_b32_e32 v17, v0
	v_mov_b32_e32 v18, v0
	v_mov_b32_e32 v19, v0
	v_mov_b32_e32 v20, v0
	v_mov_b32_e32 v21, v0
	v_mov_b32_e32 v22, v0
	v_mov_b32_e32 v23, v0
	v_mov_b32_e32 v32, v0
	v_mov_b32_e32 v33, v0
	v_mov_b32_e32 v34, v0
	v_mov_b32_e32 v35, v0
	v_mov_b32_e32 v36, v0
	v_mov_b32_e32 v37, v0
	v_mov_b32_e32 v38, v0
	v_mov_b32_e32 v39, v0
	v_mov_b32_e32 v48, v0
	v_mov_b32_e32 v49, v0
	v_mov_b32_e32 v50, v0
	v_mov_b32_e32 v51, v0
	v_mov_b32_e32 v52, v0
	v_mov_b32_e32 v53, v0
	v_mov_b32_e32 v54, v0
	v_mov_b32_e32 v55, v0
	v_mov_b32_e32 v8, v0
	v_mov_b32_e32 v9, v0
	v_mov_b32_e32 v10, v0
	v_mov_b32_e32 v11, v0
	v_mov_b32_e32 v12, v0
	v_mov_b32_e32 v13, v0
	v_mov_b32_e32 v14, v0
	v_mov_b32_e32 v15, v0
	v_mov_b32_e32 v24, v0
	v_mov_b32_e32 v25, v0
	v_mov_b32_e32 v26, v0
	v_mov_b32_e32 v27, v0
	v_mov_b32_e32 v28, v0
	v_mov_b32_e32 v29, v0
	v_mov_b32_e32 v30, v0
	v_mov_b32_e32 v31, v0
	v_mov_b32_e32 v40, v0
	v_mov_b32_e32 v41, v0
	v_mov_b32_e32 v42, v0
	v_mov_b32_e32 v43, v0
	v_mov_b32_e32 v44, v0
	v_mov_b32_e32 v45, v0
	v_mov_b32_e32 v46, v0
	v_mov_b32_e32 v47, v0
	v_mov_b32_e32 v56, v0
	v_mov_b32_e32 v57, v0
	v_mov_b32_e32 v58, v0
	v_mov_b32_e32 v59, v0
	v_mov_b32_e32 v60, v0
	v_mov_b32_e32 v61, v0
	v_mov_b32_e32 v62, v0
	v_mov_b32_e32 v63, v0
	v_mov_b32_e32 v64, v0
	v_mov_b32_e32 v65, v0
	v_mov_b32_e32 v66, v0
	v_mov_b32_e32 v67, v0
	v_mov_b32_e32 v68, v0
	v_mov_b32_e32 v69, v0
	v_mov_b32_e32 v70, v0
	v_mov_b32_e32 v71, v0
	v_mov_b32_e32 v80, v0
	v_mov_b32_e32 v81, v0
	v_mov_b32_e32 v82, v0
	v_mov_b32_e32 v83, v0
	v_mov_b32_e32 v84, v0
	v_mov_b32_e32 v85, v0
	v_mov_b32_e32 v86, v0
	v_mov_b32_e32 v87, v0
	v_mov_b32_e32 v96, v0
	v_mov_b32_e32 v97, v0
	v_mov_b32_e32 v98, v0
	v_mov_b32_e32 v99, v0
	v_mov_b32_e32 v100, v0
	v_mov_b32_e32 v101, v0
	v_mov_b32_e32 v102, v0
	v_mov_b32_e32 v103, v0
	v_mov_b32_e32 v112, v0
	v_mov_b32_e32 v113, v0
	v_mov_b32_e32 v114, v0
	v_mov_b32_e32 v115, v0
	v_mov_b32_e32 v116, v0
	v_mov_b32_e32 v117, v0
	v_mov_b32_e32 v118, v0
	v_mov_b32_e32 v119, v0
	v_mov_b32_e32 v72, v0
	v_mov_b32_e32 v73, v0
	v_mov_b32_e32 v74, v0
	v_mov_b32_e32 v75, v0
	v_mov_b32_e32 v76, v0
	v_mov_b32_e32 v77, v0
	v_mov_b32_e32 v78, v0
	v_mov_b32_e32 v79, v0
	v_mov_b32_e32 v88, v0
	v_mov_b32_e32 v89, v0
	v_mov_b32_e32 v90, v0
	v_mov_b32_e32 v91, v0
	v_mov_b32_e32 v92, v0
	v_mov_b32_e32 v93, v0
	v_mov_b32_e32 v94, v0
	v_mov_b32_e32 v95, v0
	v_mov_b32_e32 v104, v0
	v_mov_b32_e32 v105, v0
	v_mov_b32_e32 v106, v0
	v_mov_b32_e32 v107, v0
	v_mov_b32_e32 v108, v0
	v_mov_b32_e32 v109, v0
	v_mov_b32_e32 v110, v0
	v_mov_b32_e32 v111, v0
	v_mov_b32_e32 v120, v0
	v_mov_b32_e32 v121, v0
	v_mov_b32_e32 v122, v0
	v_mov_b32_e32 v123, v0
	v_mov_b32_e32 v124, v0
	v_mov_b32_e32 v125, v0
	v_mov_b32_e32 v126, v0
	v_mov_b32_e32 v127, v0
	.p2align 6
	s_nop 0
	s_nop 0
	s_nop 0
